# R2 top-4 selection: batched partial-logit LDS reads, permlane16_swap instead of ds_bpermute for the cross-row max, DPP-fused max steps
# speedup vs baseline: 1.0068x; 1.0068x over previous
; #define LAS __attribute__((address_space(3)))
; __device__ __forceinline__ void p_r2(const Args& a, LAS unsigned char* lds, volatile LAS unsigned* MISC, int l, int wg, int G, int wave, int lane, int tid) {
;     ...
;             for (int r = 0; r < 2; ++r) {
;                 if (l == 0) load_row4(xin + (size_t)(t0 + r) * D, lane, x[r]);
;                 else { v2u xw[4]; unpack_row_raw(xpre[r], lane, xw);
; #pragma unroll
;                     for (int j = 0; j < 4; ++j) x[r][j] = (f32x4){bf_lo(xw[j].x), bf_hi(xw[j].x), bf_lo(xw[j].y), bf_hi(xw[j].y)}; }
;                 unpack_row_raw(mpre[r], lane, mw[r]); }
;             if (it + 1 < 16) {
; #pragma unroll
;                 for (int r = 0; r < 2; ++r) { load_row_raw(MIX + (size_t)(t0 + 16 + r) * D, lane, mpre[r]); if (l != 0) load_row_raw(xbf + (size_t)(t0 + 16 + r) * D, lane, xpre[r]); } }
; #pragma unroll
;             for (int j = 0; j < 4; ++j) { const f32x4 g1 = *(const LAS f32x4*)(lds + R2_PAR + (0 * 256 + lane + 64 * j) * 16);
; #pragma unroll
;                 for (int r = 0; r < 2; ++r) { const f32x4 mx = (f32x4){bf_lo(mw[r][j].x), bf_hi(mw[r][j].x), bf_lo(mw[r][j].y), bf_hi(mw[r][j].y)}; x[r][j] = ALPHA * x[r][j] + (1.0f + g1) * mx; } }
;             float mean[2], rstd[2];
; #pragma unroll
;             for (int r = 0; r < 2; ++r) ln_stats(x[r], mean[r], rstd[r]);
.LBB0_836:
	v_cndmask_b32_e64 v136, v188, v136, s[44:45]
	v_cndmask_b32_e64 v138, v138, v188, s[44:45]
	v_cndmask_b32_e64 v188, v191, v133, s[44:45]
	v_cndmask_b32_e64 v133, v18, v124, s[44:45]
	v_cndmask_b32_e64 v193, v126, v18, s[44:45]
	v_add_u32_e32 v18, 0, v156
	v_cndmask_b32_e64 v137, v190, v137, s[44:45]
	v_cndmask_b32_e64 v139, v139, v190, s[44:45]
	v_cndmask_b32_e64 v190, v189, v132, s[44:45]
	v_cndmask_b32_e64 v132, v186, v125, s[44:45]
	v_cndmask_b32_e64 v192, v127, v186, s[44:45]
	v_add_u32_e32 v186, 0x14800, v18
	v_cndmask_b32_e64 v194, v187, v121, s[44:45]
	v_cndmask_b32_e64 v195, v19, v120, s[44:45]
	v_cndmask_b32_e64 v187, v123, v187, s[44:45]
	v_cndmask_b32_e64 v196, v122, v19, s[44:45]
	ds_read_b128 v[120:123], v186
	v_lshlrev_b32_e32 v18, 16, v133
	v_and_b32_e32 v19, 0xffff0000, v133
	v_and_b32_e32 v133, 0xffff0000, v137
	v_lshlrev_b32_e32 v126, 16, v136
	s_waitcnt lgkmcnt(0)
	v_pk_add_f32 v[122:123], v[122:123], 1.0 op_sel_hi:[1,0]
	v_pk_add_f32 v[124:125], v[120:121], 1.0 op_sel_hi:[1,0]
	v_lshlrev_b32_e32 v120, 16, v132
	v_and_b32_e32 v121, 0xffff0000, v132
	v_lshlrev_b32_e32 v132, 16, v137
	v_and_b32_e32 v127, 0xffff0000, v136
	v_pk_mul_f32 v[132:133], v[122:123], v[132:133]
	v_cndmask_b32_e64 v191, v135, v191, s[44:45]
	v_cndmask_b32_e64 v189, v134, v189, s[44:45]
	v_pk_mul_f32 v[120:121], v[122:123], v[120:121]
	v_pk_mul_f32 v[18:19], v[124:125], v[18:19]
	v_pk_mul_f32 v[122:123], v[124:125], v[126:127]
	v_pk_fma_f32 v[124:125], v[150:151], s[10:11], v[132:133] op_sel_hi:[1,0,1]
	ds_read_b128 v[132:135], v186 offset:1024
	v_lshlrev_b32_e32 v126, 16, v193
	v_and_b32_e32 v127, 0xffff0000, v193
	v_pk_fma_f32 v[120:121], v[146:147], s[10:11], v[120:121] op_sel_hi:[1,0,1]
	v_pk_fma_f32 v[18:19], v[144:145], s[10:11], v[18:19] op_sel_hi:[1,0,1]
	s_waitcnt lgkmcnt(0)
	v_pk_add_f32 v[134:135], v[134:135], 1.0 op_sel_hi:[1,0]
	v_pk_add_f32 v[136:137], v[132:133], 1.0 op_sel_hi:[1,0]
	v_lshlrev_b32_e32 v132, 16, v192
	v_and_b32_e32 v133, 0xffff0000, v192
	v_pk_mul_f32 v[132:133], v[134:135], v[132:133]
	v_pk_mul_f32 v[126:127], v[136:137], v[126:127]
	v_pk_fma_f32 v[132:133], v[118:119], s[10:11], v[132:133] op_sel_hi:[1,0,1]
	v_pk_fma_f32 v[126:127], v[116:117], s[10:11], v[126:127] op_sel_hi:[1,0,1]
	v_lshlrev_b32_e32 v116, 16, v138
	v_and_b32_e32 v117, 0xffff0000, v138
	v_lshlrev_b32_e32 v118, 16, v139
	v_and_b32_e32 v119, 0xffff0000, v139
	v_pk_mul_f32 v[118:119], v[134:135], v[118:119]
	v_pk_mul_f32 v[116:117], v[136:137], v[116:117]
	ds_read_b128 v[134:137], v186 offset:2048
	v_pk_fma_f32 v[116:117], v[140:141], s[10:11], v[116:117] op_sel_hi:[1,0,1]
	v_lshlrev_b32_e32 v140, 16, v194
	v_and_b32_e32 v141, 0xffff0000, v194
	v_pk_fma_f32 v[122:123], v[148:149], s[10:11], v[122:123] op_sel_hi:[1,0,1]
	s_waitcnt lgkmcnt(0)
	v_pk_add_f32 v[136:137], v[136:137], 1.0 op_sel_hi:[1,0]
	v_pk_add_f32 v[138:139], v[134:135], 1.0 op_sel_hi:[1,0]
	v_lshlrev_b32_e32 v134, 16, v195
	v_and_b32_e32 v135, 0xffff0000, v195
	v_pk_mul_f32 v[134:135], v[138:139], v[134:135]
	v_pk_mul_f32 v[140:141], v[136:137], v[140:141]
	v_pk_fma_f32 v[134:135], v[112:113], s[10:11], v[134:135] op_sel_hi:[1,0,1]
	v_pk_fma_f32 v[114:115], v[114:115], s[10:11], v[140:141] op_sel_hi:[1,0,1]
	v_lshlrev_b32_e32 v112, 16, v190
	v_and_b32_e32 v113, 0xffff0000, v190
	v_lshlrev_b32_e32 v140, 16, v188
	v_and_b32_e32 v141, 0xffff0000, v188
	v_pk_mul_f32 v[138:139], v[138:139], v[112:113]
	v_pk_mul_f32 v[112:113], v[136:137], v[140:141]
	v_pk_fma_f32 v[136:137], v[128:129], s[10:11], v[138:139] op_sel_hi:[1,0,1]
	v_pk_fma_f32 v[112:113], v[130:131], s[10:11], v[112:113] op_sel_hi:[1,0,1]
	ds_read_b128 v[128:131], v186 offset:3072
	v_lshlrev_b32_e32 v138, 16, v196
	v_and_b32_e32 v139, 0xffff0000, v196
	v_lshlrev_b32_e32 v140, 16, v187
	v_and_b32_e32 v141, 0xffff0000, v187
	s_waitcnt lgkmcnt(0)
	v_pk_add_f32 v[128:129], v[128:129], 1.0 op_sel_hi:[1,0]
	v_pk_add_f32 v[130:131], v[130:131], 1.0 op_sel_hi:[1,0]
	v_pk_mul_f32 v[138:139], v[128:129], v[138:139]
	v_pk_mul_f32 v[140:141], v[130:131], v[140:141]
	v_pk_fma_f32 v[146:147], v[104:105], s[10:11], v[138:139] op_sel_hi:[1,0,1]
	v_lshlrev_b32_e32 v104, 16, v189
	v_and_b32_e32 v105, 0xffff0000, v189
	v_lshlrev_b32_e32 v138, 16, v191
	v_and_b32_e32 v139, 0xffff0000, v191
	v_pk_mul_f32 v[128:129], v[128:129], v[104:105]
	v_pk_mul_f32 v[104:105], v[130:131], v[138:139]
	v_pk_fma_f32 v[144:145], v[108:109], s[10:11], v[128:129] op_sel_hi:[1,0,1]
	v_pk_fma_f32 v[104:105], v[110:111], s[10:11], v[104:105] op_sel_hi:[1,0,1]
	v_pk_mov_b32 v[108:109], v[18:19], v[120:121] op_sel:[1,0]
	v_mov_b32_e32 v110, v18
	v_mov_b32_e32 v111, v121
	v_pk_add_f32 v[108:109], v[108:109], v[110:111]
	v_pk_mov_b32 v[110:111], v[126:127], v[132:133] op_sel:[1,0]
	v_mov_b32_e32 v128, v126
	v_mov_b32_e32 v129, v133
	v_pk_add_f32 v[110:111], v[110:111], v[128:129]
	v_pk_fma_f32 v[106:107], v[106:107], s[10:11], v[140:141] op_sel_hi:[1,0,1]
	v_add_f32_e32 v108, v108, v109
	v_pk_add_f32 v[110:111], v[110:111], v[110:111] op_sel:[0,1] op_sel_hi:[1,0]
	v_add_f32_e32 v108, 0, v108
	v_add_f32_e32 v128, v134, v135
	v_add_f32_e32 v130, v114, v115
	v_mov_b32_e32 v109, v146
	v_mov_b32_e32 v111, v147
	v_mov_b32_e32 v129, v106
	v_mov_b32_e32 v131, v107
	v_pk_add_f32 v[108:109], v[108:109], v[110:111]
	v_pk_add_f32 v[110:111], v[128:129], v[130:131]
	v_pk_fma_f32 v[118:119], v[142:143], s[10:11], v[118:119] op_sel_hi:[1,0,1]
	v_pk_add_f32 v[108:109], v[108:109], v[110:111]
	v_mov_b32_e32 v139, v105
	v_add_f32_e32 v108, v108, v109
	s_nop 1
	v_add_f32_dpp v108, v108, v108 quad_perm:[1,0,3,2] row_mask:0xf bank_mask:0xf bound_ctrl:1
	s_nop 1
; __device__ __forceinline__ void ln_stats(const f32x4 (&v)[4], float& mean, float& rstd) {
;     float s = 0.f;
; #pragma unroll
;     for (int j = 0; j < 4; ++j) s += (v[j][0] + v[j][1]) + (v[j][2] + v[j][3]);
;     mean = wave_sum(s) * (1.f / D); float q = 0.f;
; #pragma unroll
;     for (int j = 0; j < 4; ++j) { const f32x4 d = v[j] - mean; q += (d[0] * d[0] + d[1] * d[1]) + (d[2] * d[2] + d[3] * d[3]); }
;     rstd = rsqrtf(wave_sum(q) * (1.f / D) + LN_EPS);
; }
; __device__ __forceinline__ void p_r2(const Args& a, LAS unsigned char* lds, volatile LAS unsigned* MISC, int l, int wg, int G, int wave, int lane, int tid) {
;     ...
;             float mean[2], rstd[2];
; #pragma unroll
;             for (int r = 0; r < 2; ++r) ln_stats(x[r], mean[r], rstd[r]);
	v_add_f32_dpp v108, v108, v108 quad_perm:[2,3,0,1] row_mask:0xf bank_mask:0xf bound_ctrl:1
	s_nop 1
	v_add_f32_dpp v108, v108, v108 row_half_mirror row_mask:0xf bank_mask:0xf bound_ctrl:1
	s_nop 1
	v_add_f32_dpp v108, v108, v108 row_mirror row_mask:0xf bank_mask:0xf bound_ctrl:1
	s_nop 0
	v_readlane_b32 s4, v108, 16
	v_readlane_b32 s9, v108, 48
	v_readlane_b32 s2, v108, 0
	v_readlane_b32 s3, v108, 32
	v_mov_b32_e32 v108, s4
	v_mov_b32_e32 v109, s9
	v_pk_add_f32 v[108:109], s[2:3], v[108:109]
	s_nop 0
	v_add_f32_e32 v138, v108, v109
	v_fmamk_f32 v19, v138, 0xba800000, v19
	v_fmac_f32_e32 v18, 0xba800000, v138
	v_fmamk_f32 v121, v138, 0xba800000, v121
	v_fmac_f32_e32 v120, 0xba800000, v138
	v_pk_mul_f32 v[108:109], v[120:121], v[120:121]
	v_pk_mul_f32 v[110:111], v[18:19], v[18:19]
	v_fmamk_f32 v127, v138, 0xba800000, v127
	v_pk_mov_b32 v[128:129], v[110:111], v[108:109] op_sel:[1,0]
	v_mov_b32_e32 v111, v109
	v_pk_add_f32 v[108:109], v[128:129], v[110:111]
	v_fmac_f32_e32 v126, 0xba800000, v138
	v_fmamk_f32 v133, v138, 0xba800000, v133
	v_fmac_f32_e32 v132, 0xba800000, v138
	v_pk_add_f32 v[108:109], v[108:109], v[108:109] op_sel_hi:[0,1]
	v_pk_mul_f32 v[110:111], v[132:133], v[132:133]
	v_pk_mul_f32 v[128:129], v[126:127], v[126:127]
	v_fmac_f32_e32 v134, 0xba800000, v138
	v_pk_mov_b32 v[130:131], v[128:129], v[110:111] op_sel:[1,0]
	v_mov_b32_e32 v129, v111
	v_fmamk_f32 v135, v138, 0xba800000, v135
	v_fmac_f32_e32 v114, 0xba800000, v138
	v_mul_f32_e32 v108, v134, v134
	v_pk_add_f32 v[110:111], v[130:131], v[128:129]
	v_fmamk_f32 v115, v138, 0xba800000, v115
	v_pk_fma_f32 v[128:129], v[134:135], v[134:135], v[108:109] op_sel_hi:[1,1,0]
	v_mul_f32_e32 v108, v114, v114
	v_pk_add_f32 v[110:111], v[110:111], v[110:111] op_sel_hi:[0,1]
	v_pk_fma_f32 v[130:131], v[114:115], v[114:115], v[108:109] op_sel_hi:[1,1,0]
	v_fmamk_f32 v107, v138, 0xba800000, v107
	v_fmac_f32_e32 v106, 0xba800000, v138
	v_fmamk_f32 v147, v138, 0xba800000, v147
	v_fmac_f32_e32 v146, 0xba800000, v138
	v_mul_f32_e32 v128, v146, v146
	v_mul_f32_e32 v130, v147, v147
	v_mul_f32_e32 v108, v106, v106
	v_mul_f32_e32 v110, v107, v107
	v_pk_add_f32 v[128:129], v[128:129], v[130:131]
	v_pk_add_f32 v[108:109], v[108:109], v[110:111]
	v_pk_mov_b32 v[110:111], v[122:123], v[124:125] op_sel:[1,0]
	v_pk_add_f32 v[108:109], v[128:129], v[108:109]
	v_mov_b32_e32 v128, v122
	v_mov_b32_e32 v129, v125
	v_pk_add_f32 v[110:111], v[110:111], v[128:129]
	v_pk_mov_b32 v[128:129], v[116:117], v[118:119] op_sel:[1,0]
	v_mov_b32_e32 v130, v116
	v_mov_b32_e32 v131, v119
	v_pk_add_f32 v[128:129], v[128:129], v[130:131]
	v_add_f32_e32 v110, v110, v111
	v_pk_add_f32 v[128:129], v[128:129], v[128:129] op_sel:[0,1] op_sel_hi:[1,0]
	v_add_f32_e32 v110, 0, v110
	v_add_f32_e32 v130, v136, v137
	v_add_f32_e32 v138, v112, v113
	v_mov_b32_e32 v111, v144
	v_mov_b32_e32 v129, v145
	v_mov_b32_e32 v131, v104
	v_pk_add_f32 v[110:111], v[110:111], v[128:129]
	v_pk_add_f32 v[128:129], v[130:131], v[138:139]
	v_add_f32_e32 v108, v108, v109
	v_pk_add_f32 v[110:111], v[110:111], v[128:129]
	s_nop 0
	v_add_f32_dpp v108, v108, v108 quad_perm:[1,0,3,2] row_mask:0xf bank_mask:0xf bound_ctrl:1
	v_add_f32_e32 v110, v110, v111
	s_nop 0
	v_add_f32_dpp v108, v108, v108 quad_perm:[2,3,0,1] row_mask:0xf bank_mask:0xf bound_ctrl:1
	v_add_f32_dpp v110, v110, v110 quad_perm:[1,0,3,2] row_mask:0xf bank_mask:0xf bound_ctrl:1
	s_nop 0
	v_add_f32_dpp v108, v108, v108 row_half_mirror row_mask:0xf bank_mask:0xf bound_ctrl:1
	v_add_f32_dpp v110, v110, v110 quad_perm:[2,3,0,1] row_mask:0xf bank_mask:0xf bound_ctrl:1
	s_nop 0
	v_add_f32_dpp v108, v108, v108 row_mirror row_mask:0xf bank_mask:0xf bound_ctrl:1
	v_add_f32_dpp v110, v110, v110 row_half_mirror row_mask:0xf bank_mask:0xf bound_ctrl:1
	v_readlane_b32 s4, v108, 16
	v_readlane_b32 s9, v108, 48
	v_add_f32_dpp v110, v110, v110 row_mirror row_mask:0xf bank_mask:0xf bound_ctrl:1
	v_readlane_b32 s2, v108, 0
	v_readlane_b32 s3, v108, 32
	v_mov_b32_e32 v108, s4
	v_mov_b32_e32 v109, s9
	v_readlane_b32 s4, v110, 16
	v_readlane_b32 s9, v110, 48
	v_pk_add_f32 v[108:109], s[2:3], v[108:109]
	v_readlane_b32 s2, v110, 0
	v_readlane_b32 s3, v110, 32
	v_mov_b32_e32 v110, s4
	v_mov_b32_e32 v111, s9
	v_pk_add_f32 v[110:111], s[2:3], v[110:111]
	s_nop 0
	v_add_f32_e32 v140, v110, v111
	v_fmamk_f32 v123, v140, 0xba800000, v123
	v_fmac_f32_e32 v122, 0xba800000, v140
	v_fmamk_f32 v125, v140, 0xba800000, v125
	v_fmac_f32_e32 v124, 0xba800000, v140
	v_pk_mul_f32 v[110:111], v[124:125], v[124:125]
	v_pk_mul_f32 v[128:129], v[122:123], v[122:123]
	v_fmamk_f32 v117, v140, 0xba800000, v117
	v_pk_mov_b32 v[130:131], v[128:129], v[110:111] op_sel:[1,0]
	v_mov_b32_e32 v129, v111
	v_pk_add_f32 v[110:111], v[130:131], v[128:129]
	v_fmac_f32_e32 v116, 0xba800000, v140
	v_fmamk_f32 v119, v140, 0xba800000, v119
	v_fmac_f32_e32 v118, 0xba800000, v140
	v_pk_add_f32 v[110:111], v[110:111], v[110:111] op_sel_hi:[0,1]
	v_pk_mul_f32 v[128:129], v[118:119], v[118:119]
	v_pk_mul_f32 v[130:131], v[116:117], v[116:117]
	v_fmac_f32_e32 v136, 0xba800000, v140
	v_pk_mov_b32 v[138:139], v[130:131], v[128:129] op_sel:[1,0]
	v_mov_b32_e32 v131, v129
	v_fmamk_f32 v137, v140, 0xba800000, v137
	v_fmac_f32_e32 v112, 0xba800000, v140
	v_mul_f32_e32 v110, v136, v136
	v_pk_add_f32 v[128:129], v[138:139], v[130:131]
	v_fmamk_f32 v113, v140, 0xba800000, v113
	v_pk_fma_f32 v[130:131], v[136:137], v[136:137], v[110:111] op_sel_hi:[1,1,0]
	v_mul_f32_e32 v110, v112, v112
	v_pk_add_f32 v[128:129], v[128:129], v[128:129] op_sel_hi:[0,1]
	v_pk_fma_f32 v[138:139], v[112:113], v[112:113], v[110:111] op_sel_hi:[1,1,0]
	v_fmamk_f32 v105, v140, 0xba800000, v105
; #define GAS __attribute__((address_space(1)))
; #define LAS __attribute__((address_space(3)))
; __device__ __forceinline__ unsigned pk2(float lo, float hi) { typedef __bf16 bf2_t __attribute__((ext_vector_type(2))); const f32x2 v = {lo, hi}; return __builtin_bit_cast(unsigned, __builtin_convertvector(v, bf2_t)); }
; __device__ __forceinline__ unsigned dpp_swap1(unsigned v) { return (unsigned)__builtin_amdgcn_update_dpp(0, (int)v, 0xB1, 0xF, 0xF, true); }
; __device__ __forceinline__ void store_row_pk(bf16* rowp, int lane, const v2u (&o)[4]) {
;     const bool odd = (lane & 1) != 0; bf16* p = rowp + 4 * (lane & ~1) + (odd ? 256 : 0);
; #pragma unroll
;     for (int pr = 0; pr < 2; ++pr) { const v2u a = o[2 * pr], b = o[2 * pr + 1], send = odd ? a : b; v2u recv; recv.x = dpp_swap1(send.x); recv.y = dpp_swap1(send.y);
;         const v4u w = odd ? (v4u){recv.x, recv.y, b.x, b.y} : (v4u){a.x, a.y, recv.x, recv.y};
;         *(GAS v4u*)(p + 512 * pr) = w; }
; }
; __device__ __forceinline__ void p_r2(const Args& a, LAS unsigned char* lds, volatile LAS unsigned* MISC, int l, int wg, int G, int wave, int lane, int tid) {
;     ...
;             for (int r = 0; r < 2; ++r) ln_stats(x[r], mean[r], rstd[r]);
; #pragma unroll
;             for (int j = 0; j < 4; ++j) { const f32x4 g = *(const LAS f32x4*)(lds + R2_PAR + (1 * 256 + lane + 64 * j) * 16), bb = *(const LAS f32x4*)(lds + R2_PAR + (2 * 256 + lane + 64 * j) * 16);
; #pragma unroll
;                 for (int r = 0; r < 2; ++r) { x[r][j] = (x[r][j] - mean[r]) * rstd[r] * g + bb; ob[r][j].x = pk2(x[r][j][0], x[r][j][1]); ob[r][j].y = pk2(x[r][j][2], x[r][j][3]); } }
; #pragma unroll
;             for (int r = 0; r < 2; ++r) store_row_pk(X1 + (size_t)(t0 + r) * D, lane, ob[r]);
	v_fmac_f32_e32 v104, 0xba800000, v140
	v_fmamk_f32 v145, v140, 0xba800000, v145
	v_fmac_f32_e32 v144, 0xba800000, v140
	v_mul_f32_e32 v130, v144, v144
	v_mul_f32_e32 v138, v145, v145
	v_mul_f32_e32 v110, v104, v104
	v_mul_f32_e32 v128, v105, v105
	v_pk_add_f32 v[130:131], v[130:131], v[138:139]
	v_pk_add_f32 v[110:111], v[110:111], v[128:129]
	v_mov_b32_e32 v129, v108
	v_pk_add_f32 v[110:111], v[130:131], v[110:111]
	s_nop 0
	v_add_f32_e32 v110, v110, v111
	s_nop 1
	v_add_f32_dpp v110, v110, v110 quad_perm:[1,0,3,2] row_mask:0xf bank_mask:0xf bound_ctrl:1
	s_nop 1
	v_add_f32_dpp v110, v110, v110 quad_perm:[2,3,0,1] row_mask:0xf bank_mask:0xf bound_ctrl:1
	s_nop 1
	v_add_f32_dpp v110, v110, v110 row_half_mirror row_mask:0xf bank_mask:0xf bound_ctrl:1
	s_nop 1
	v_add_f32_dpp v110, v110, v110 row_mirror row_mask:0xf bank_mask:0xf bound_ctrl:1
	s_nop 0
	v_readlane_b32 s4, v110, 16
	v_readlane_b32 s9, v110, 48
	v_readlane_b32 s2, v110, 0
	v_readlane_b32 s3, v110, 32
	v_mov_b32_e32 v110, s4
	v_mov_b32_e32 v111, s9
	v_pk_add_f32 v[110:111], s[2:3], v[110:111]
	s_mov_b32 s2, 0x3727c5ac
	v_mov_b32_e32 v128, v110
	v_mov_b32_e32 v108, v111
	v_pk_add_f32 v[108:109], v[128:129], v[108:109]
	v_mov_b64_e32 v[142:143], s[2:3]
	v_pk_fma_f32 v[108:109], v[108:109], s[70:71], v[142:143] op_sel_hi:[1,0,0]
	s_ashr_i32 s9, s8, 31
	v_mul_f32_e32 v110, 0x4b800000, v109
	v_cmp_gt_f32_e64 s[54:55], s68, v109
	v_cmp_gt_f32_e32 vcc, s68, v108
	s_lshl_b64 s[2:3], s[8:9], 11
	v_cndmask_b32_e64 v109, v109, v110, s[54:55]
	v_rsq_f32_e32 v109, v109
	s_nop 0
	v_mul_f32_e32 v110, 0x45800000, v109
	v_cndmask_b32_e64 v188, v109, v110, s[54:55]
	v_mul_f32_e32 v109, 0x4b800000, v108
	v_cndmask_b32_e32 v108, v108, v109, vcc
	v_rsq_f32_e32 v108, v108
	v_pk_mul_f32 v[18:19], v[18:19], v[188:189] op_sel_hi:[1,0]
	v_pk_mul_f32 v[120:121], v[120:121], v[188:189] op_sel_hi:[1,0]
	v_mul_f32_e32 v109, 0x45800000, v108
	v_cndmask_b32_e32 v190, v108, v109, vcc
	ds_read_b128 v[108:111], v186 offset:4096
	ds_read_b128 v[148:151], v186 offset:8192
	s_waitcnt lgkmcnt(0)
	v_pk_fma_f32 v[138:139], v[120:121], v[110:111], v[150:151]
	v_pk_fma_f32 v[140:141], v[18:19], v[108:109], v[148:149]
	v_pk_mul_f32 v[18:19], v[122:123], v[190:191] op_sel_hi:[1,0]
	v_pk_mul_f32 v[120:121], v[124:125], v[190:191] op_sel_hi:[1,0]
	v_pk_fma_f32 v[130:131], v[108:109], v[18:19], v[148:149]
	v_pk_fma_f32 v[128:129], v[110:111], v[120:121], v[150:151]
	ds_read_b128 v[108:111], v186 offset:5120
	ds_read_b128 v[120:123], v186 offset:9216
	v_cvt_pk_bf16_f32 v189, v138, v139
	v_cvt_pk_bf16_f32 v191, v130, v131
	v_pk_mul_f32 v[18:19], v[126:127], v[188:189] op_sel_hi:[1,0]
	v_pk_mul_f32 v[124:125], v[132:133], v[188:189] op_sel_hi:[1,0]
	s_waitcnt lgkmcnt(0)
	v_pk_fma_f32 v[126:127], v[18:19], v[108:109], v[120:121]
	v_pk_mul_f32 v[18:19], v[116:117], v[190:191] op_sel_hi:[1,0]
	v_pk_mul_f32 v[116:117], v[118:119], v[190:191] op_sel_hi:[1,0]
	v_pk_fma_f32 v[124:125], v[124:125], v[110:111], v[122:123]
	v_pk_fma_f32 v[118:119], v[110:111], v[116:117], v[122:123]
	v_pk_fma_f32 v[120:121], v[108:109], v[18:19], v[120:121]
	ds_read_b128 v[108:111], v186 offset:6144
	ds_read_b128 v[148:151], v186 offset:10240
	v_pk_mul_f32 v[18:19], v[134:135], v[188:189] op_sel_hi:[1,0]
	v_pk_mul_f32 v[114:115], v[114:115], v[188:189] op_sel_hi:[1,0]
	v_pk_mul_f32 v[112:113], v[112:113], v[190:191] op_sel_hi:[1,0]
	v_cvt_pk_bf16_f32 v187, v140, v141
	s_waitcnt lgkmcnt(0)
	v_pk_fma_f32 v[116:117], v[18:19], v[108:109], v[148:149]
	v_pk_mul_f32 v[18:19], v[136:137], v[190:191] op_sel_hi:[1,0]
	v_pk_fma_f32 v[114:115], v[114:115], v[110:111], v[150:151]
	v_pk_fma_f32 v[110:111], v[110:111], v[112:113], v[150:151]
	v_pk_fma_f32 v[112:113], v[108:109], v[18:19], v[148:149]
	ds_read_b128 v[132:135], v186 offset:7168
	ds_read_b128 v[148:151], v186 offset:11264
	v_cvt_pk_bf16_f32 v193, v126, v127
	v_cvt_pk_bf16_f32 v194, v124, v125
	v_pk_mul_f32 v[18:19], v[146:147], v[188:189] op_sel_hi:[1,0]
	v_pk_mul_f32 v[122:123], v[144:145], v[190:191] op_sel_hi:[1,0]
	v_pk_mul_f32 v[106:107], v[106:107], v[188:189] op_sel_hi:[1,0]
	s_waitcnt lgkmcnt(0)
	v_pk_fma_f32 v[108:109], v[18:19], v[132:133], v[148:149]
	v_pk_mul_f32 v[18:19], v[104:105], v[190:191] op_sel_hi:[1,0]
	v_pk_fma_f32 v[104:105], v[132:133], v[122:123], v[148:149]
	v_cndmask_b32_e64 v132, v189, v194, s[44:45]
	v_cndmask_b32_e64 v133, v187, v193, s[44:45]
	v_pk_fma_f32 v[106:107], v[106:107], v[134:135], v[150:151]
	v_mov_b32_dpp v132, v132 quad_perm:[1,0,3,2] row_mask:0xf bank_mask:0xf bound_ctrl:1
	v_mov_b32_dpp v148, v133 quad_perm:[1,0,3,2] row_mask:0xf bank_mask:0xf bound_ctrl:1
	v_cvt_pk_bf16_f32 v197, v116, v117
	v_cvt_pk_bf16_f32 v202, v114, v115
	v_cvt_pk_bf16_f32 v146, v108, v109
	v_cvt_pk_bf16_f32 v147, v106, v107
	v_pk_fma_f32 v[18:19], v[134:135], v[18:19], v[150:151]
	v_lshl_add_u64 v[122:123], v[160:161], 0, s[2:3]
	v_cndmask_b32_e64 v135, v194, v132, s[44:45]
	v_cndmask_b32_e64 v134, v193, v148, s[44:45]
	v_cndmask_b32_e64 v133, v132, v189, s[44:45]
	v_cndmask_b32_e64 v132, v148, v187, s[44:45]
	global_store_dwordx4 v[122:123], v[132:135], off
	v_cvt_pk_bf16_f32 v192, v128, v129
	v_cvt_pk_bf16_f32 v195, v120, v121
	v_cndmask_b32_e64 v132, v202, v147, s[44:45]
	v_cndmask_b32_e64 v133, v197, v146, s[44:45]
	v_cvt_pk_bf16_f32 v196, v118, v119
	v_mov_b32_dpp v132, v132 quad_perm:[1,0,3,2] row_mask:0xf bank_mask:0xf bound_ctrl:1
	v_mov_b32_dpp v148, v133 quad_perm:[1,0,3,2] row_mask:0xf bank_mask:0xf bound_ctrl:1
	v_cndmask_b32_e64 v135, v147, v132, s[44:45]
	v_cndmask_b32_e64 v134, v146, v148, s[44:45]
	v_cndmask_b32_e64 v133, v132, v202, s[44:45]
	v_cndmask_b32_e64 v132, v148, v197, s[44:45]
; #define GAS __attribute__((address_space(1)))
; __device__ __forceinline__ unsigned pk2(float lo, float hi) { typedef __bf16 bf2_t __attribute__((ext_vector_type(2))); const f32x2 v = {lo, hi}; return __builtin_bit_cast(unsigned, __builtin_convertvector(v, bf2_t)); }
; __device__ __forceinline__ unsigned dpp_swap1(unsigned v) { return (unsigned)__builtin_amdgcn_update_dpp(0, (int)v, 0xB1, 0xF, 0xF, true); }
; __device__ __forceinline__ void store_row_pk(bf16* rowp, int lane, const v2u (&o)[4]) {
;     const bool odd = (lane & 1) != 0; bf16* p = rowp + 4 * (lane & ~1) + (odd ? 256 : 0);
; #pragma unroll
;     for (int pr = 0; pr < 2; ++pr) { const v2u a = o[2 * pr], b = o[2 * pr + 1], send = odd ? a : b; v2u recv; recv.x = dpp_swap1(send.x); recv.y = dpp_swap1(send.y);
;         const v4u w = odd ? (v4u){recv.x, recv.y, b.x, b.y} : (v4u){a.x, a.y, recv.x, recv.y};
;         *(GAS v4u*)(p + 512 * pr) = w; }
; }
; __device__ __forceinline__ void p_r2(const Args& a, LAS unsigned char* lds, volatile LAS unsigned* MISC, int l, int wg, int G, int wave, int lane, int tid) {
;     ...
;                 for (int r = 0; r < 2; ++r) { x[r][j] = (x[r][j] - mean[r]) * rstd[r] * g + bb; ob[r][j].x = pk2(x[r][j][0], x[r][j][1]); ob[r][j].y = pk2(x[r][j][2], x[r][j][3]); } }
; #pragma unroll
;             for (int r = 0; r < 2; ++r) store_row_pk(X1 + (size_t)(t0 + r) * D, lane, ob[r]);
; #pragma unroll
;             for (int r = 0; r < 2; ++r) ln_stats(x[r], mean[r], rstd[r]);
	s_add_i32 s2, s8, 1
	global_store_dwordx4 v[122:123], v[132:135], off offset:1024
	s_ashr_i32 s3, s2, 31
	s_lshl_b64 s[34:35], s[2:3], 11
	v_cndmask_b32_e64 v132, v192, v196, s[44:45]
	v_cndmask_b32_e64 v133, v191, v195, s[44:45]
	v_cvt_pk_bf16_f32 v136, v112, v113
	v_mov_b32_dpp v132, v132 quad_perm:[1,0,3,2] row_mask:0xf bank_mask:0xf bound_ctrl:1
	v_mov_b32_dpp v146, v133 quad_perm:[1,0,3,2] row_mask:0xf bank_mask:0xf bound_ctrl:1
	v_cvt_pk_bf16_f32 v137, v110, v111
	v_cvt_pk_bf16_f32 v144, v104, v105
	v_cvt_pk_bf16_f32 v145, v18, v19
	v_lshl_add_u64 v[122:123], v[160:161], 0, s[34:35]
	v_cndmask_b32_e64 v135, v196, v132, s[44:45]
	v_cndmask_b32_e64 v134, v195, v146, s[44:45]
	v_cndmask_b32_e64 v133, v132, v192, s[44:45]
	v_cndmask_b32_e64 v132, v146, v191, s[44:45]
	global_store_dwordx4 v[122:123], v[132:135], off
	s_lshl_b64 s[8:9], s[8:9], 10
	s_lshl_b64 s[2:3], s[2:3], 10
	v_cndmask_b32_e64 v132, v137, v145, s[44:45]
	v_cndmask_b32_e64 v133, v136, v144, s[44:45]
	s_nop 0
	v_mov_b32_dpp v132, v132 quad_perm:[1,0,3,2] row_mask:0xf bank_mask:0xf bound_ctrl:1
	v_mov_b32_dpp v146, v133 quad_perm:[1,0,3,2] row_mask:0xf bank_mask:0xf bound_ctrl:1
	v_cndmask_b32_e64 v135, v145, v132, s[44:45]
	v_cndmask_b32_e64 v134, v144, v146, s[44:45]
	v_cndmask_b32_e64 v133, v132, v137, s[44:45]
	v_cndmask_b32_e64 v132, v146, v136, s[44:45]
	global_store_dwordx4 v[122:123], v[132:135], off offset:1024
	v_pk_mov_b32 v[122:123], v[140:141], v[138:139] op_sel:[1,0]
	v_add_f32_e32 v136, v114, v115
	v_mov_b32_e32 v132, v140
	v_mov_b32_e32 v133, v139
	v_pk_add_f32 v[122:123], v[122:123], v[132:133]
	v_pk_mov_b32 v[132:133], v[126:127], v[124:125] op_sel:[1,0]
	v_mov_b32_e32 v134, v126
	v_mov_b32_e32 v135, v125
	v_pk_add_f32 v[132:133], v[132:133], v[134:135]
	v_add_f32_e32 v122, v122, v123
	v_pk_add_f32 v[132:133], v[132:133], v[132:133] op_sel:[0,1] op_sel_hi:[1,0]
	v_add_f32_e32 v122, 0, v122
	v_add_f32_e32 v134, v116, v117
	v_mov_b32_e32 v123, v108
	v_mov_b32_e32 v133, v109
	v_mov_b32_e32 v135, v106
	v_mov_b32_e32 v137, v107
	v_pk_add_f32 v[122:123], v[122:123], v[132:133]
	v_pk_add_f32 v[132:133], v[134:135], v[136:137]
	v_add_f32_e32 v145, v110, v111
	v_pk_add_f32 v[122:123], v[122:123], v[132:133]
	s_nop 0
	v_add_f32_e32 v122, v122, v123
	s_nop 1
	v_add_f32_dpp v122, v122, v122 quad_perm:[1,0,3,2] row_mask:0xf bank_mask:0xf bound_ctrl:1
	s_nop 1
	v_add_f32_dpp v122, v122, v122 quad_perm:[2,3,0,1] row_mask:0xf bank_mask:0xf bound_ctrl:1
	s_nop 1
	v_add_f32_dpp v122, v122, v122 row_half_mirror row_mask:0xf bank_mask:0xf bound_ctrl:1
	s_nop 1
	v_add_f32_dpp v122, v122, v122 row_mirror row_mask:0xf bank_mask:0xf bound_ctrl:1
	s_nop 0
	v_readlane_b32 s4, v122, 16
	v_readlane_b32 s25, v122, 48
	v_readlane_b32 s34, v122, 0
	v_readlane_b32 s35, v122, 32
	v_mov_b32_e32 v122, s4
	v_mov_b32_e32 v123, s25
	v_pk_add_f32 v[122:123], s[34:35], v[122:123]
	s_nop 0
	v_add_f32_e32 v144, v122, v123
	v_fmamk_f32 v141, v144, 0xba800000, v141
	v_fmac_f32_e32 v140, 0xba800000, v144
	v_fmamk_f32 v139, v144, 0xba800000, v139
	v_fmac_f32_e32 v138, 0xba800000, v144
	v_pk_mul_f32 v[122:123], v[138:139], v[138:139]
	v_pk_mul_f32 v[132:133], v[140:141], v[140:141]
	v_fmamk_f32 v127, v144, 0xba800000, v127
	v_pk_mov_b32 v[134:135], v[132:133], v[122:123] op_sel:[1,0]
	v_mov_b32_e32 v133, v123
	v_pk_add_f32 v[122:123], v[134:135], v[132:133]
	v_fmac_f32_e32 v126, 0xba800000, v144
	v_fmamk_f32 v125, v144, 0xba800000, v125
	v_fmac_f32_e32 v124, 0xba800000, v144
	v_pk_add_f32 v[122:123], v[122:123], v[122:123] op_sel_hi:[0,1]
	v_pk_mul_f32 v[132:133], v[124:125], v[124:125]
	v_pk_mul_f32 v[134:135], v[126:127], v[126:127]
	v_fmac_f32_e32 v116, 0xba800000, v144
	v_pk_mov_b32 v[136:137], v[134:135], v[132:133] op_sel:[1,0]
	v_mov_b32_e32 v135, v133
	v_fmamk_f32 v117, v144, 0xba800000, v117
	v_fmac_f32_e32 v114, 0xba800000, v144
	v_mul_f32_e32 v122, v116, v116
	v_pk_add_f32 v[132:133], v[136:137], v[134:135]
	v_fmamk_f32 v115, v144, 0xba800000, v115
	v_pk_fma_f32 v[134:135], v[116:117], v[116:117], v[122:123] op_sel_hi:[1,1,0]
	v_mul_f32_e32 v122, v114, v114
	v_pk_add_f32 v[132:133], v[132:133], v[132:133] op_sel_hi:[0,1]
	v_pk_fma_f32 v[136:137], v[114:115], v[114:115], v[122:123] op_sel_hi:[1,1,0]
	v_fmamk_f32 v107, v144, 0xba800000, v107
	v_fmac_f32_e32 v106, 0xba800000, v144
	v_fmamk_f32 v109, v144, 0xba800000, v109
	v_fmac_f32_e32 v108, 0xba800000, v144
	v_mul_f32_e32 v134, v108, v108
	v_mul_f32_e32 v136, v109, v109
	v_mul_f32_e32 v122, v106, v106
	v_mul_f32_e32 v132, v107, v107
	v_pk_add_f32 v[134:135], v[134:135], v[136:137]
	v_pk_add_f32 v[122:123], v[122:123], v[132:133]
	v_pk_mov_b32 v[132:133], v[130:131], v[128:129] op_sel:[1,0]
	v_pk_add_f32 v[122:123], v[134:135], v[122:123]
	v_mov_b32_e32 v134, v130
	v_mov_b32_e32 v135, v129
	v_pk_add_f32 v[132:133], v[132:133], v[134:135]
	v_pk_mov_b32 v[134:135], v[120:121], v[118:119] op_sel:[1,0]
	v_mov_b32_e32 v136, v120
	v_mov_b32_e32 v137, v119
	v_pk_add_f32 v[134:135], v[134:135], v[136:137]
	v_add_f32_e32 v132, v132, v133
	v_pk_add_f32 v[134:135], v[134:135], v[134:135] op_sel_hi:[0,1]
	v_add_f32_e32 v133, 0, v132
	v_add_f32_e32 v137, v112, v113
	v_mov_b32_e32 v136, v104
	v_mov_b32_e32 v144, v105
	v_mov_b32_e32 v134, v18
	v_mov_b32_e32 v132, v19
	v_pk_add_f32 v[136:137], v[136:137], v[144:145]
	v_pk_add_f32 v[132:133], v[134:135], v[132:133]
	v_add_f32_e32 v122, v122, v123
	v_pk_add_f32 v[132:133], v[136:137], v[132:133]
	s_nop 0
	v_add_f32_dpp v122, v122, v122 quad_perm:[1,0,3,2] row_mask:0xf bank_mask:0xf bound_ctrl:1
	v_add_f32_e32 v132, v132, v133
	s_nop 0
	v_add_f32_dpp v122, v122, v122 quad_perm:[2,3,0,1] row_mask:0xf bank_mask:0xf bound_ctrl:1
; #define LAS __attribute__((address_space(3)))
; __device__ __forceinline__ void ln_stats(const f32x4 (&v)[4], float& mean, float& rstd) {
;     float s = 0.f;
; #pragma unroll
;     for (int j = 0; j < 4; ++j) s += (v[j][0] + v[j][1]) + (v[j][2] + v[j][3]);
;     mean = wave_sum(s) * (1.f / D); float q = 0.f;
; #pragma unroll
;     for (int j = 0; j < 4; ++j) { const f32x4 d = v[j] - mean; q += (d[0] * d[0] + d[1] * d[1]) + (d[2] * d[2] + d[3] * d[3]); }
;     rstd = rsqrtf(wave_sum(q) * (1.f / D) + LN_EPS);
; }
; __device__ __forceinline__ void p_r2(const Args& a, LAS unsigned char* lds, volatile LAS unsigned* MISC, int l, int wg, int G, int wave, int lane, int tid) {
;     ...
;             for (int r = 0; r < 2; ++r) ln_stats(x[r], mean[r], rstd[r]);
; #pragma unroll
;             for (int j = 0; j < 4; ++j) { const f32x4 s1 = *(const LAS f32x4*)(lds + R2_PAR + (3 * 256 + lane + 64 * j) * 16), s0 = *(const LAS f32x4*)(lds + R2_PAR + (4 * 256 + lane + 64 * j) * 16);
; #pragma unroll
;                 for (int r = 0; r < 2; ++r) { u[r][j] = (x[r][j] - mean[r]) * rstd[r] * (1.0f + s1) + s0;
	v_add_f32_dpp v132, v132, v132 quad_perm:[1,0,3,2] row_mask:0xf bank_mask:0xf bound_ctrl:1
	s_nop 0
	v_add_f32_dpp v122, v122, v122 row_half_mirror row_mask:0xf bank_mask:0xf bound_ctrl:1
	v_add_f32_dpp v132, v132, v132 quad_perm:[2,3,0,1] row_mask:0xf bank_mask:0xf bound_ctrl:1
	s_nop 0
	v_add_f32_dpp v122, v122, v122 row_mirror row_mask:0xf bank_mask:0xf bound_ctrl:1
	v_add_f32_dpp v132, v132, v132 row_half_mirror row_mask:0xf bank_mask:0xf bound_ctrl:1
	v_readlane_b32 s4, v122, 16
	v_readlane_b32 s25, v122, 48
	v_add_f32_dpp v132, v132, v132 row_mirror row_mask:0xf bank_mask:0xf bound_ctrl:1
	v_readlane_b32 s34, v122, 0
	v_readlane_b32 s35, v122, 32
	v_mov_b32_e32 v122, s4
	v_mov_b32_e32 v123, s25
	v_readlane_b32 s4, v132, 16
	v_readlane_b32 s25, v132, 48
	v_pk_add_f32 v[122:123], s[34:35], v[122:123]
	v_readlane_b32 s34, v132, 0
	v_readlane_b32 s35, v132, 32
	v_mov_b32_e32 v132, s4
	v_mov_b32_e32 v133, s25
	v_pk_add_f32 v[132:133], s[34:35], v[132:133]
	s_nop 0
	v_add_f32_e32 v146, v132, v133
	v_fmamk_f32 v131, v146, 0xba800000, v131
	v_fmac_f32_e32 v130, 0xba800000, v146
	v_fmamk_f32 v129, v146, 0xba800000, v129
	v_fmac_f32_e32 v128, 0xba800000, v146
	v_pk_mul_f32 v[132:133], v[128:129], v[128:129]
	v_pk_mul_f32 v[134:135], v[130:131], v[130:131]
	v_fmamk_f32 v121, v146, 0xba800000, v121
	v_pk_mov_b32 v[136:137], v[134:135], v[132:133] op_sel:[1,0]
	v_mov_b32_e32 v135, v133
	v_pk_add_f32 v[132:133], v[136:137], v[134:135]
	v_fmac_f32_e32 v120, 0xba800000, v146
	v_fmamk_f32 v119, v146, 0xba800000, v119
	v_fmac_f32_e32 v118, 0xba800000, v146
	v_pk_add_f32 v[132:133], v[132:133], v[132:133] op_sel_hi:[0,1]
	v_pk_mul_f32 v[134:135], v[118:119], v[118:119]
	v_pk_mul_f32 v[136:137], v[120:121], v[120:121]
	v_fmac_f32_e32 v112, 0xba800000, v146
	v_pk_mov_b32 v[144:145], v[136:137], v[134:135] op_sel:[1,0]
	v_mov_b32_e32 v137, v135
	v_fmamk_f32 v113, v146, 0xba800000, v113
	v_fmac_f32_e32 v110, 0xba800000, v146
	v_mul_f32_e32 v132, v112, v112
	v_pk_add_f32 v[134:135], v[144:145], v[136:137]
	v_fmamk_f32 v111, v146, 0xba800000, v111
	v_pk_fma_f32 v[136:137], v[112:113], v[112:113], v[132:133] op_sel_hi:[1,1,0]
	v_mul_f32_e32 v132, v110, v110
	v_pk_add_f32 v[134:135], v[134:135], v[134:135] op_sel_hi:[0,1]
	v_pk_fma_f32 v[144:145], v[110:111], v[110:111], v[132:133] op_sel_hi:[1,1,0]
	v_fmamk_f32 v19, v146, 0xba800000, v19
	v_fmac_f32_e32 v18, 0xba800000, v146
	v_fmamk_f32 v105, v146, 0xba800000, v105
	v_fmac_f32_e32 v104, 0xba800000, v146
	v_mul_f32_e32 v136, v104, v104
	v_mul_f32_e32 v144, v105, v105
	v_mul_f32_e32 v132, v18, v18
	v_mul_f32_e32 v134, v19, v19
	v_pk_add_f32 v[136:137], v[136:137], v[144:145]
	v_pk_add_f32 v[132:133], v[132:133], v[134:135]
	v_mov_b32_e32 v135, v122
	v_pk_add_f32 v[132:133], v[136:137], v[132:133]
	s_nop 0
	v_add_f32_e32 v132, v132, v133
	s_nop 1
	v_add_f32_dpp v132, v132, v132 quad_perm:[1,0,3,2] row_mask:0xf bank_mask:0xf bound_ctrl:1
	s_nop 1
	v_add_f32_dpp v132, v132, v132 quad_perm:[2,3,0,1] row_mask:0xf bank_mask:0xf bound_ctrl:1
	s_nop 1
	v_add_f32_dpp v132, v132, v132 row_half_mirror row_mask:0xf bank_mask:0xf bound_ctrl:1
	s_nop 1
	v_add_f32_dpp v132, v132, v132 row_mirror row_mask:0xf bank_mask:0xf bound_ctrl:1
	s_nop 0
	v_readlane_b32 s4, v132, 16
	v_readlane_b32 s25, v132, 48
	v_readlane_b32 s34, v132, 0
	v_readlane_b32 s35, v132, 32
	v_mov_b32_e32 v132, s4
	v_mov_b32_e32 v133, s25
	v_pk_add_f32 v[132:133], s[34:35], v[132:133]
	s_nop 0
	v_mov_b32_e32 v134, v132
	v_mov_b32_e32 v122, v133
	v_pk_add_f32 v[122:123], v[134:135], v[122:123]
	s_nop 0
	v_pk_fma_f32 v[122:123], v[122:123], s[70:71], v[142:143] op_sel_hi:[1,0,0]
	ds_read_b128 v[134:137], v186 offset:12288
	ds_read_b128 v[142:145], v186 offset:16384
	v_mul_f32_e32 v132, 0x4b800000, v123
	v_cmp_gt_f32_e64 s[54:55], s68, v123
	v_cmp_gt_f32_e32 vcc, s68, v122
	s_waitcnt lgkmcnt(1)
	v_pk_add_f32 v[134:135], v[134:135], 1.0 op_sel_hi:[1,0]
	v_cndmask_b32_e64 v123, v123, v132, s[54:55]
	v_rsq_f32_e32 v123, v123
	v_pk_add_f32 v[136:137], v[136:137], 1.0 op_sel_hi:[1,0]
	v_mul_f32_e32 v132, 0x45800000, v123
	v_cndmask_b32_e64 v132, v123, v132, s[54:55]
	v_mul_f32_e32 v123, 0x4b800000, v122
	v_cndmask_b32_e32 v122, v122, v123, vcc
	v_rsq_f32_e32 v122, v122
	v_pk_mul_f32 v[140:141], v[140:141], v[132:133] op_sel_hi:[1,0]
	v_pk_mul_f32 v[138:139], v[138:139], v[132:133] op_sel_hi:[1,0]
	s_waitcnt lgkmcnt(0)
; __device__ __forceinline__ unsigned pk4_fp8(float a, float b, float c, float d) { int w = 0; w = __builtin_amdgcn_cvt_pk_fp8_f32(a, b, w, false); w = __builtin_amdgcn_cvt_pk_fp8_f32(c, d, w, true); return (unsigned)w; }
; #define LAS __attribute__((address_space(3)))
; __device__ __forceinline__ unsigned pk4_fp8(float a, float b, float c, float d) { int w = 0; w = __builtin_amdgcn_cvt_pk_fp8_f32(a, b, w, false); w = __builtin_amdgcn_cvt_pk_fp8_f32(c, d, w, true); return (unsigned)w; }
; __device__ __forceinline__ void p_r2(const Args& a, LAS unsigned char* lds, volatile LAS unsigned* MISC, int l, int wg, int G, int wave, int lane, int tid) {
;     ...
;             for (int j = 0; j < 4; ++j) { const f32x4 s1 = *(const LAS f32x4*)(lds + R2_PAR + (3 * 256 + lane + 64 * j) * 16), s0 = *(const LAS f32x4*)(lds + R2_PAR + (4 * 256 + lane + 64 * j) * 16);
; #pragma unroll
;                 for (int r = 0; r < 2; ++r) { u[r][j] = (x[r][j] - mean[r]) * rstd[r] * (1.0f + s1) + s0;
;                     uq[r][j] = pk4_fp8(u[r][j][0] * F8_SA1, u[r][j][1] * F8_SA1, u[r][j][2] * F8_SA1, u[r][j][3] * F8_SA1);
;                     const h16x2 h0 = __builtin_amdgcn_cvt_pkrtz(u[r][j][0], u[r][j][1]), h1 = __builtin_amdgcn_cvt_pkrtz(u[r][j][2], u[r][j][3]);
;                     const h16x2 l0 = __builtin_amdgcn_cvt_pkrtz(u[r][j][0] - (float)h0[0], u[r][j][1] - (float)h0[1]), l1 = __builtin_amdgcn_cvt_pkrtz(u[r][j][2] - (float)h1[0], u[r][j][3] - (float)h1[1]);
;                     const int row = 2 * wave + r, off = row * 2048 + ((((lane >> 1) + 32 * j) ^ (row & 15)) << 4) + 8 * (lane & 1);
;                     *(LAS v2u*)(lds + R2_UH + off) = (v2u){__builtin_bit_cast(unsigned, h0), __builtin_bit_cast(unsigned, h1)};
;                     *(LAS v2u*)(lds + R2_UL + off) = (v2u){__builtin_bit_cast(unsigned, l0), __builtin_bit_cast(unsigned, l1)}; } }
	v_pk_fma_f32 v[140:141], v[140:141], v[134:135], v[142:143]
	v_mul_f32_e32 v123, 0x45800000, v122
	v_cndmask_b32_e32 v122, v122, v123, vcc
	v_mul_f32_e32 v133, 4.0, v140
	v_mul_f32_e32 v146, 4.0, v141
	v_mov_b32_e32 v123, v16
	v_cvt_pk_fp8_f32 v123, v133, v146
	v_cvt_pkrtz_f16_f32 v146, v140, v141
	v_cvt_f32_f16_e32 v133, v146
	v_pk_fma_f32 v[138:139], v[138:139], v[136:137], v[144:145]
	v_sub_f32_e32 v133, v140, v133
	v_cvt_f32_f16_sdwa v140, v146 dst_sel:DWORD dst_unused:UNUSED_PAD src0_sel:WORD_1
	v_mul_f32_e32 v147, 4.0, v138
	v_mul_f32_e32 v148, 4.0, v139
	v_cvt_pk_fp8_f32 v123, v147, v148 op_sel:[0,0,1]
	v_cvt_pkrtz_f16_f32 v147, v138, v139
	v_sub_f32_e32 v140, v141, v140
	v_cvt_pkrtz_f16_f32 v140, v133, v140
	v_cvt_f32_f16_e32 v133, v147
	v_pk_mul_f32 v[130:131], v[130:131], v[122:123] op_sel_hi:[1,0]
	v_pk_mul_f32 v[128:129], v[128:129], v[122:123] op_sel_hi:[1,0]
	v_pk_fma_f32 v[130:131], v[134:135], v[130:131], v[142:143]
	v_sub_f32_e32 v133, v138, v133
	v_cvt_f32_f16_sdwa v138, v147 dst_sel:DWORD dst_unused:UNUSED_PAD src0_sel:WORD_1
	v_pk_fma_f32 v[136:137], v[136:137], v[128:129], v[144:145]
	v_mul_f32_e32 v129, 4.0, v130
	v_mov_b32_e32 v128, v16
	v_sub_f32_e32 v138, v139, v138
	v_cvt_pkrtz_f16_f32 v141, v133, v138
	v_mul_f32_e32 v133, 4.0, v131
	v_cvt_pk_fp8_f32 v128, v129, v133
	v_mul_f32_e32 v134, 4.0, v136
	v_mul_f32_e32 v135, 4.0, v137
	ds_write2st64_b64 v172, v[146:147], v[140:141] offset1:64
	v_cvt_pk_fp8_f32 v128, v134, v135 op_sel:[0,0,1]
	v_cvt_pkrtz_f16_f32 v134, v130, v131
	v_cvt_f32_f16_e32 v129, v134
	v_cvt_pkrtz_f16_f32 v135, v136, v137
	v_pk_mul_f32 v[126:127], v[126:127], v[132:133] op_sel_hi:[1,0]
	v_pk_mul_f32 v[124:125], v[124:125], v[132:133] op_sel_hi:[1,0]
	v_sub_f32_e32 v129, v130, v129
	v_cvt_f32_f16_sdwa v130, v134 dst_sel:DWORD dst_unused:UNUSED_PAD src0_sel:WORD_1
	v_pk_mul_f32 v[120:121], v[120:121], v[122:123] op_sel_hi:[1,0]
	v_pk_mul_f32 v[118:119], v[118:119], v[122:123] op_sel_hi:[1,0]
	v_pk_mul_f32 v[112:113], v[112:113], v[122:123] op_sel_hi:[1,0]
	v_sub_f32_e32 v130, v131, v130
	v_cvt_pkrtz_f16_f32 v130, v129, v130
	v_cvt_f32_f16_e32 v129, v135
	v_cvt_f32_f16_sdwa v131, v135 dst_sel:DWORD dst_unused:UNUSED_PAD src0_sel:WORD_1
	v_pk_mul_f32 v[110:111], v[110:111], v[122:123] op_sel_hi:[1,0]
	v_pk_mul_f32 v[104:105], v[104:105], v[122:123] op_sel_hi:[1,0]
	v_sub_f32_e32 v129, v136, v129
	v_sub_f32_e32 v131, v137, v131
	v_cvt_pkrtz_f16_f32 v131, v129, v131
	ds_write2st64_b64 v173, v[134:135], v[130:131] offset1:64
	ds_read_b128 v[134:137], v186 offset:13312
	ds_read_b128 v[138:141], v186 offset:17408
	v_pk_mul_f32 v[18:19], v[18:19], v[122:123] op_sel_hi:[1,0]
	s_waitcnt lgkmcnt(1)
	v_pk_add_f32 v[134:135], v[134:135], 1.0 op_sel_hi:[1,0]
	v_pk_add_f32 v[130:131], v[136:137], 1.0 op_sel_hi:[1,0]
	s_waitcnt lgkmcnt(0)
	v_pk_fma_f32 v[126:127], v[126:127], v[134:135], v[138:139]
	v_pk_fma_f32 v[136:137], v[124:125], v[130:131], v[140:141]
	v_mul_f32_e32 v125, 4.0, v126
	v_mul_f32_e32 v129, 4.0, v127
	v_mov_b32_e32 v124, v16
	v_cvt_pk_fp8_f32 v124, v125, v129
	v_mul_f32_e32 v133, 4.0, v136
	v_mul_f32_e32 v142, 4.0, v137
	v_cvt_pkrtz_f16_f32 v143, v136, v137
	v_cvt_pk_fp8_f32 v124, v133, v142 op_sel:[0,0,1]
	v_cvt_pkrtz_f16_f32 v142, v126, v127
	v_cvt_f32_f16_e32 v125, v142
	v_pk_fma_f32 v[120:121], v[134:135], v[120:121], v[138:139]
	v_pk_fma_f32 v[118:119], v[130:131], v[118:119], v[140:141]
	v_mov_b32_e32 v130, v16
	v_sub_f32_e32 v125, v126, v125
	v_cvt_f32_f16_sdwa v126, v142 dst_sel:DWORD dst_unused:UNUSED_PAD src0_sel:WORD_1
	v_mul_f32_e32 v129, 4.0, v119
	v_pk_mul_f32 v[116:117], v[116:117], v[132:133] op_sel_hi:[1,0]
	v_mov_b32_e32 v131, v16
	v_sub_f32_e32 v126, v127, v126
	v_cvt_pkrtz_f16_f32 v126, v125, v126
	v_cvt_f32_f16_e32 v125, v143
	v_cvt_f32_f16_sdwa v127, v143 dst_sel:DWORD dst_unused:UNUSED_PAD src0_sel:WORD_1
	v_pk_mul_f32 v[114:115], v[114:115], v[132:133] op_sel_hi:[1,0]
	v_pk_mul_f32 v[108:109], v[108:109], v[132:133] op_sel_hi:[1,0]
	v_sub_f32_e32 v125, v136, v125
	v_sub_f32_e32 v127, v137, v127
	v_cvt_pkrtz_f16_f32 v127, v125, v127
	ds_write2st64_b64 v174, v[142:143], v[126:127] offset1:64
	v_mul_f32_e32 v125, 4.0, v120
	v_mul_f32_e32 v126, 4.0, v121
	v_cvt_pk_fp8_f32 v130, v125, v126
	v_cvt_pkrtz_f16_f32 v126, v120, v121
	v_cvt_f32_f16_e32 v125, v126
	v_mul_f32_e32 v127, 4.0, v118
	v_cvt_pk_fp8_f32 v130, v127, v129 op_sel:[0,0,1]
	v_cvt_pkrtz_f16_f32 v127, v118, v119
	v_sub_f32_e32 v120, v120, v125
	v_cvt_f32_f16_sdwa v125, v126 dst_sel:DWORD dst_unused:UNUSED_PAD src0_sel:WORD_1
	v_pk_mul_f32 v[106:107], v[106:107], v[132:133] op_sel_hi:[1,0]
	v_sub_f32_e32 v121, v121, v125
	v_cvt_pkrtz_f16_f32 v120, v120, v121
	v_cvt_f32_f16_e32 v121, v127
	v_sub_f32_e32 v118, v118, v121
	v_cvt_f32_f16_sdwa v121, v127 dst_sel:DWORD dst_unused:UNUSED_PAD src0_sel:WORD_1
	v_sub_f32_e32 v119, v119, v121
	v_cvt_pkrtz_f16_f32 v121, v118, v119
	ds_write2st64_b64 v175, v[126:127], v[120:121] offset1:64
	ds_read_b128 v[118:121], v186 offset:14336
	ds_read_b128 v[134:137], v186 offset:18432
	s_waitcnt lgkmcnt(1)
	v_pk_add_f32 v[118:119], v[118:119], 1.0 op_sel_hi:[1,0]
	s_waitcnt lgkmcnt(0)
; #define GAS __attribute__((address_space(1)))
; #define LAS __attribute__((address_space(3)))
; __device__ __forceinline__ void store_row_q8(unsigned char* rowp, int lane, const unsigned (&d)[4]) {
;     const bool o1 = (lane & 1) != 0, o2 = (lane & 2) != 0;
;     unsigned p[2][2];
; #pragma unroll
;     for (int cc = 0; cc < 2; ++cc) { const unsigned keep = o1 ? d[2 * cc + 1] : d[2 * cc], send = o1 ? d[2 * cc] : d[2 * cc + 1], recv = dpp_swap1(send); p[cc][0] = o1 ? recv : keep; p[cc][1] = o1 ? keep : recv; }
;     const unsigned s0 = o2 ? p[0][0] : p[1][0], s1 = o2 ? p[0][1] : p[1][1], r0 = dpp_swap2(s0), r1 = dpp_swap2(s1);
;     const v4u w = o2 ? (v4u){r0, r1, p[1][0], p[1][1]} : (v4u){p[0][0], p[0][1], r0, r1};
;     *(GAS v4u*)(rowp + 16 * (lane >> 2) + 256 * (lane & 3)) = w;
; }
; __device__ __forceinline__ void p_r2(const Args& a, LAS unsigned char* lds, volatile LAS unsigned* MISC, int l, int wg, int G, int wave, int lane, int tid) {
;     ...
;             for (int j = 0; j < 4; ++j) { const f32x4 s1 = *(const LAS f32x4*)(lds + R2_PAR + (3 * 256 + lane + 64 * j) * 16), s0 = *(const LAS f32x4*)(lds + R2_PAR + (4 * 256 + lane + 64 * j) * 16);
; #pragma unroll
;                 for (int r = 0; r < 2; ++r) { u[r][j] = (x[r][j] - mean[r]) * rstd[r] * (1.0f + s1) + s0;
;                     uq[r][j] = pk4_fp8(u[r][j][0] * F8_SA1, u[r][j][1] * F8_SA1, u[r][j][2] * F8_SA1, u[r][j][3] * F8_SA1);
;                     const h16x2 h0 = __builtin_amdgcn_cvt_pkrtz(u[r][j][0], u[r][j][1]), h1 = __builtin_amdgcn_cvt_pkrtz(u[r][j][2], u[r][j][3]);
;                     const h16x2 l0 = __builtin_amdgcn_cvt_pkrtz(u[r][j][0] - (float)h0[0], u[r][j][1] - (float)h0[1]), l1 = __builtin_amdgcn_cvt_pkrtz(u[r][j][2] - (float)h1[0], u[r][j][3] - (float)h1[1]);
;                     const int row = 2 * wave + r, off = row * 2048 + ((((lane >> 1) + 32 * j) ^ (row & 15)) << 4) + 8 * (lane & 1);
;                     *(LAS v2u*)(lds + R2_UH + off) = (v2u){__builtin_bit_cast(unsigned, h0), __builtin_bit_cast(unsigned, h1)};
;                     *(LAS v2u*)(lds + R2_UL + off) = (v2u){__builtin_bit_cast(unsigned, l0), __builtin_bit_cast(unsigned, l1)}; } }
; #pragma unroll
;             for (int r = 0; r < 2; ++r) store_row_q8(U8 + (size_t)(t0 + r) * D, lane, uq[r]);
;             __syncthreads();
	v_pk_fma_f32 v[116:117], v[116:117], v[118:119], v[134:135]
	v_pk_add_f32 v[120:121], v[120:121], 1.0 op_sel_hi:[1,0]
	v_mul_f32_e32 v125, 4.0, v116
	v_mul_f32_e32 v126, 4.0, v117
	v_cvt_pk_fp8_f32 v131, v125, v126
	v_cvt_pkrtz_f16_f32 v126, v116, v117
	v_cvt_f32_f16_e32 v125, v126
	v_pk_fma_f32 v[114:115], v[114:115], v[120:121], v[136:137]
	v_pk_fma_f32 v[112:113], v[112:113], v[118:119], v[134:135]
	v_mul_f32_e32 v127, 4.0, v114
	v_sub_f32_e32 v116, v116, v125
	v_cvt_f32_f16_sdwa v125, v126 dst_sel:DWORD dst_unused:UNUSED_PAD src0_sel:WORD_1
	v_mul_f32_e32 v129, 4.0, v115
	v_cvt_pk_fp8_f32 v131, v127, v129 op_sel:[0,0,1]
	v_cvt_pkrtz_f16_f32 v127, v114, v115
	v_sub_f32_e32 v117, v117, v125
	v_cvt_pkrtz_f16_f32 v116, v116, v117
	v_cvt_f32_f16_e32 v117, v127
	v_pk_fma_f32 v[110:111], v[110:111], v[120:121], v[136:137]
	v_mov_b32_e32 v120, v16
	v_sub_f32_e32 v114, v114, v117
	v_cvt_f32_f16_sdwa v117, v127 dst_sel:DWORD dst_unused:UNUSED_PAD src0_sel:WORD_1
	v_sub_f32_e32 v115, v115, v117
	v_cvt_pkrtz_f16_f32 v117, v114, v115
	v_mul_f32_e32 v114, 4.0, v112
	v_mul_f32_e32 v115, 4.0, v113
	v_cvt_pk_fp8_f32 v120, v114, v115
	ds_write2st64_b64 v176, v[126:127], v[116:117] offset1:64
	v_mul_f32_e32 v116, 4.0, v110
	v_mul_f32_e32 v117, 4.0, v111
	v_cvt_pkrtz_f16_f32 v114, v112, v113
	v_cvt_pk_fp8_f32 v120, v116, v117 op_sel:[0,0,1]
	v_cvt_f32_f16_e32 v116, v114
	v_cvt_pkrtz_f16_f32 v115, v110, v111
	v_mov_b32_e32 v126, v16
	v_sub_f32_e32 v112, v112, v116
	v_cvt_f32_f16_sdwa v116, v114 dst_sel:DWORD dst_unused:UNUSED_PAD src0_sel:WORD_1
	v_sub_f32_e32 v113, v113, v116
	v_cvt_pkrtz_f16_f32 v112, v112, v113
	v_cvt_f32_f16_e32 v113, v115
	v_sub_f32_e32 v110, v110, v113
	v_cvt_f32_f16_sdwa v113, v115 dst_sel:DWORD dst_unused:UNUSED_PAD src0_sel:WORD_1
	v_sub_f32_e32 v111, v111, v113
	v_cvt_pkrtz_f16_f32 v113, v110, v111
	ds_write2st64_b64 v177, v[114:115], v[112:113] offset1:64
	ds_read_b128 v[110:113], v186 offset:15360
	ds_read_b128 v[114:117], v186 offset:19456
	s_waitcnt lgkmcnt(1)
	v_pk_add_f32 v[110:111], v[110:111], 1.0 op_sel_hi:[1,0]
	s_waitcnt lgkmcnt(0)
	v_pk_fma_f32 v[108:109], v[108:109], v[110:111], v[114:115]
	v_pk_add_f32 v[112:113], v[112:113], 1.0 op_sel_hi:[1,0]
	v_mul_f32_e32 v118, 4.0, v108
	v_mul_f32_e32 v119, 4.0, v109
	v_cvt_pk_fp8_f32 v126, v118, v119
	v_pk_fma_f32 v[106:107], v[106:107], v[112:113], v[116:117]
	v_cvt_pkrtz_f16_f32 v118, v108, v109
	v_mul_f32_e32 v121, 4.0, v106
	v_mul_f32_e32 v125, 4.0, v107
	v_cvt_pk_fp8_f32 v126, v121, v125 op_sel:[0,0,1]
	v_cvt_f32_f16_e32 v121, v118
	v_cvt_pkrtz_f16_f32 v119, v106, v107
	v_pk_fma_f32 v[104:105], v[104:105], v[110:111], v[114:115]
	v_mov_b32_e32 v110, v16
	v_sub_f32_e32 v108, v108, v121
	v_cvt_f32_f16_sdwa v121, v118 dst_sel:DWORD dst_unused:UNUSED_PAD src0_sel:WORD_1
	v_pk_fma_f32 v[18:19], v[18:19], v[112:113], v[116:117]
	v_sub_f32_e32 v109, v109, v121
	v_cvt_pkrtz_f16_f32 v108, v108, v109
	v_cvt_f32_f16_e32 v109, v119
	v_sub_f32_e32 v106, v106, v109
	v_cvt_f32_f16_sdwa v109, v119 dst_sel:DWORD dst_unused:UNUSED_PAD src0_sel:WORD_1
	v_sub_f32_e32 v107, v107, v109
	v_cvt_pkrtz_f16_f32 v109, v106, v107
	v_mul_f32_e32 v106, 4.0, v104
	v_mul_f32_e32 v107, 4.0, v105
	v_cvt_pk_fp8_f32 v110, v106, v107
	ds_write2st64_b64 v178, v[118:119], v[108:109] offset1:64
	v_mul_f32_e32 v108, 4.0, v18
	v_mul_f32_e32 v109, 4.0, v19
	v_cvt_pkrtz_f16_f32 v106, v104, v105
	v_cvt_pk_fp8_f32 v110, v108, v109 op_sel:[0,0,1]
	v_cvt_f32_f16_e32 v108, v106
	v_cvt_pkrtz_f16_f32 v107, v18, v19
	v_sub_f32_e32 v104, v104, v108
	v_cvt_f32_f16_sdwa v108, v106 dst_sel:DWORD dst_unused:UNUSED_PAD src0_sel:WORD_1
	v_sub_f32_e32 v105, v105, v108
	v_cvt_pkrtz_f16_f32 v104, v104, v105
	v_cvt_f32_f16_e32 v105, v107
	v_sub_f32_e32 v18, v18, v105
	v_cvt_f32_f16_sdwa v105, v107 dst_sel:DWORD dst_unused:UNUSED_PAD src0_sel:WORD_1
	v_sub_f32_e32 v19, v19, v105
	v_cvt_pkrtz_f16_f32 v105, v18, v19
	ds_write2st64_b64 v179, v[106:107], v[104:105] offset1:64
	v_cndmask_b32_e64 v18, v123, v124, s[44:45]
	v_cndmask_b32_e64 v104, v131, v126, s[44:45]
	s_nop 0
	v_mov_b32_dpp v18, v18 quad_perm:[1,0,3,2] row_mask:0xf bank_mask:0xf bound_ctrl:1
	v_mov_b32_dpp v104, v104 quad_perm:[1,0,3,2] row_mask:0xf bank_mask:0xf bound_ctrl:1
	v_cndmask_b32_e64 v19, v18, v123, s[44:45]
	v_cndmask_b32_e64 v18, v124, v18, s[44:45]
	v_cndmask_b32_e64 v105, v104, v131, s[44:45]
	v_cndmask_b32_e64 v104, v126, v104, s[44:45]
	v_cndmask_b32_e64 v106, v19, v105, s[46:47]
	v_cndmask_b32_e64 v107, v18, v104, s[46:47]
	s_nop 0
	v_mov_b32_dpp v108, v106 quad_perm:[2,3,0,1] row_mask:0xf bank_mask:0xf bound_ctrl:1
	v_mov_b32_dpp v109, v107 quad_perm:[2,3,0,1] row_mask:0xf bank_mask:0xf bound_ctrl:1
	v_cndmask_b32_e64 v107, v104, v109, s[46:47]
	v_cndmask_b32_e64 v106, v105, v108, s[46:47]
	v_cndmask_b32_e64 v105, v109, v18, s[46:47]
	v_cndmask_b32_e64 v104, v108, v19, s[46:47]
	v_lshl_add_u64 v[18:19], v[164:165], 0, s[8:9]
	global_store_dwordx4 v[18:19], v[104:107], off
	v_cndmask_b32_e64 v18, v128, v130, s[44:45]
	s_nop 0
	v_cndmask_b32_e64 v104, v120, v110, s[44:45]
	v_mov_b32_dpp v18, v18 quad_perm:[1,0,3,2] row_mask:0xf bank_mask:0xf bound_ctrl:1
	v_cndmask_b32_e64 v19, v18, v128, s[44:45]
	v_mov_b32_dpp v104, v104 quad_perm:[1,0,3,2] row_mask:0xf bank_mask:0xf bound_ctrl:1
	v_cndmask_b32_e64 v18, v130, v18, s[44:45]
	v_cndmask_b32_e64 v105, v104, v120, s[44:45]
	v_cndmask_b32_e64 v104, v110, v104, s[44:45]
	v_cndmask_b32_e64 v106, v19, v105, s[46:47]
	v_cndmask_b32_e64 v107, v18, v104, s[46:47]
	s_nop 0
	v_mov_b32_dpp v108, v106 quad_perm:[2,3,0,1] row_mask:0xf bank_mask:0xf bound_ctrl:1
	v_mov_b32_dpp v109, v107 quad_perm:[2,3,0,1] row_mask:0xf bank_mask:0xf bound_ctrl:1
	v_cndmask_b32_e64 v107, v104, v109, s[46:47]
	v_cndmask_b32_e64 v106, v105, v108, s[46:47]
	v_cndmask_b32_e64 v105, v109, v18, s[46:47]
	v_cndmask_b32_e64 v104, v108, v19, s[46:47]
	v_lshl_add_u64 v[18:19], v[164:165], 0, s[2:3]
	global_store_dwordx4 v[18:19], v[104:107], off
	s_waitcnt lgkmcnt(0)
	s_barrier
; #define LAS __attribute__((address_space(3)))
; __device__ __forceinline__ void p_r2(const Args& a, LAS unsigned char* lds, volatile LAS unsigned* MISC, int l, int wg, int G, int wave, int lane, int tid) {
;     ...
;             f32x4 acc[2] = {(f32x4){0.f, 0.f, 0.f, 0.f}, (f32x4){0.f, 0.f, 0.f, 0.f}};
; #pragma unroll
;             for (int s = 0; s < 4; ++s) { const int off = fr * 2048 + (((4 * (4 * wave + s) + fq) ^ fr) << 4);
;                 const f16x8 ah = *(const LAS f16x8*)(lds + R2_UH + off), al = *(const LAS f16x8*)(lds + R2_UL + off);
; #pragma unroll
;                 for (int nt = 0; nt < 2; ++nt) { acc[nt] = __builtin_amdgcn_mfma_f32_16x16x32_f16(ah, bh[s][nt], acc[nt], 0, 0, 0); acc[nt] = __builtin_amdgcn_mfma_f32_16x16x32_f16(ah, bl[s][nt], acc[nt], 0, 0, 0);
;                     acc[nt] = __builtin_amdgcn_mfma_f32_16x16x32_f16(al, bh[s][nt], acc[nt], 0, 0, 0); } }
; #pragma unroll
;             for (int nt = 0; nt < 2; ++nt)
; #pragma unroll
;                 for (int r = 0; r < 4; ++r) PART[(wave * 16 + 4 * fq + r) * 32 + 16 * nt + fr] = acc[nt][r];
;             __syncthreads();
;             float sgm = rbias;
; #pragma unroll
;             for (int w = 0; w < 8; ++w) sgm += PART[(w * 16 + (tid >> 5)) * 32 + (tid & 31)];
;             { const int half = lane >> 5, ee = lane & 31; float lg = sgm;
;               int si[4]; float sv[4];
; #pragma unroll
;               for (int k = 0; k < 4; ++k) { float mx = row16_max(lg); mx = fmaxf(mx, __shfl_xor(mx, 16)); const unsigned long long bal = __ballot(lg == mx);
;                   const unsigned bits = half ? (unsigned)(bal >> 32) : (unsigned)bal; si[k] = __ffs((int)bits) - 1; sv[k] = mx; if (ee == si[k]) lg = -3.0e38f; }
;               const float e1 = ex2((sv[1] - sv[0]) * LOG2E), e2 = ex2((sv[2] - sv[0]) * LOG2E), e3 = ex2((sv[3] - sv[0]) * LOG2E), inv = 1.0f / (1.0f + e1 + e2 + e3);
;               if (ee == 0) { const int t = tb + 2 * wave + half;
;                   *(LAS v4i*)(lds + R2_TOP + (t - 256 * chunk) * 16) = (v4i){si[0], si[1], si[2], si[3]}; *(LAS f32x4*)(lds + R2_TOP + 4096 + (t - 256 * chunk) * 16) = (f32x4){inv, e1 * inv, e2 * inv, e3 * inv};
; #pragma unroll
;                   for (int k = 0; k < 4; ++k) __hip_atomic_fetch_add((LAS unsigned*)(MISC + MW_HIST + si[k]), 1u, __ATOMIC_RELAXED, __HIP_MEMORY_SCOPE_WORKGROUP); } }
	ds_read_b128 v[104:107], v180
	ds_read_b128 v[108:111], v180 offset:32768
	s_waitcnt lgkmcnt(1)
	v_mfma_f32_16x16x32_f16 v[112:115], v[104:107], v[0:3], 0
	v_mfma_f32_16x16x32_f16 v[116:119], v[104:107], v[8:11], 0
	v_mfma_f32_16x16x32_f16 v[112:115], v[104:107], v[4:7], v[112:115]
	v_mfma_f32_16x16x32_f16 v[104:107], v[104:107], v[12:15], v[116:119]
	s_waitcnt lgkmcnt(0)
	v_mfma_f32_16x16x32_f16 v[112:115], v[108:111], v[0:3], v[112:115]
	v_mfma_f32_16x16x32_f16 v[104:107], v[108:111], v[8:11], v[104:107]
	ds_read_b128 v[108:111], v181
	s_nop 1
	ds_read_b128 v[116:119], v181 offset:32768
	s_waitcnt lgkmcnt(1)
	v_mfma_f32_16x16x32_f16 v[112:115], v[108:111], v[20:23], v[112:115]
	v_mfma_f32_16x16x32_f16 v[104:107], v[108:111], v[28:31], v[104:107]
	v_mfma_f32_16x16x32_f16 v[112:115], v[108:111], v[24:27], v[112:115]
	v_mfma_f32_16x16x32_f16 v[104:107], v[108:111], v[32:35], v[104:107]
	s_waitcnt lgkmcnt(0)
	v_mfma_f32_16x16x32_f16 v[112:115], v[116:119], v[20:23], v[112:115]
	v_mfma_f32_16x16x32_f16 v[104:107], v[116:119], v[28:31], v[104:107]
	ds_read_b128 v[108:111], v182
	ds_read_b128 v[116:119], v182 offset:32768
	s_waitcnt lgkmcnt(1)
	v_mfma_f32_16x16x32_f16 v[112:115], v[108:111], v[36:39], v[112:115]
	v_mfma_f32_16x16x32_f16 v[104:107], v[108:111], v[44:47], v[104:107]
	v_mfma_f32_16x16x32_f16 v[112:115], v[108:111], v[40:43], v[112:115]
	v_mfma_f32_16x16x32_f16 v[104:107], v[108:111], v[48:51], v[104:107]
	s_waitcnt lgkmcnt(0)
	v_mfma_f32_16x16x32_f16 v[112:115], v[116:119], v[36:39], v[112:115]
	v_mfma_f32_16x16x32_f16 v[104:107], v[116:119], v[44:47], v[104:107]
	ds_read_b128 v[108:111], v183
	ds_read_b128 v[116:119], v183 offset:32768
	s_waitcnt lgkmcnt(1)
	v_mfma_f32_16x16x32_f16 v[112:115], v[108:111], v[52:55], v[112:115]
	v_mfma_f32_16x16x32_f16 v[104:107], v[108:111], v[60:63], v[104:107]
	v_mfma_f32_16x16x32_f16 v[112:115], v[108:111], v[56:59], v[112:115]
	v_mfma_f32_16x16x32_f16 v[104:107], v[108:111], v[68:71], v[104:107]
	s_waitcnt lgkmcnt(0)
	v_mfma_f32_16x16x32_f16 v[112:115], v[116:119], v[52:55], v[112:115]
	v_mfma_f32_16x16x32_f16 v[104:107], v[116:119], v[60:63], v[104:107]
	s_nop 7
	ds_write2_b32 v184, v112, v104 offset1:16
	ds_write2_b32 v184, v113, v105 offset0:32 offset1:48
	ds_write2_b32 v184, v114, v106 offset0:64 offset1:80
	ds_write2_b32 v184, v115, v107 offset0:96 offset1:112
	s_waitcnt lgkmcnt(0)
	s_barrier
	ds_read2st64_b32 v[18:19], v65 offset1:8
	ds_read2st64_b32 v[104:105], v65 offset0:16 offset1:24
	ds_read2st64_b32 v[106:107], v65 offset0:32 offset1:40
	ds_read2st64_b32 v[108:109], v65 offset0:48 offset1:56
	s_waitcnt lgkmcnt(3)
	v_add_f32_e32 v18, v167, v18
	v_add_f32_e32 v18, v18, v19
	s_waitcnt lgkmcnt(2)
	v_add_f32_e32 v18, v18, v104
	v_add_f32_e32 v18, v18, v105
	s_waitcnt lgkmcnt(1)
	v_add_f32_e32 v18, v18, v106
	v_add_f32_e32 v18, v18, v107
	s_waitcnt lgkmcnt(0)
	v_add_f32_e32 v18, v18, v108
	v_add_f32_e32 v19, v18, v109
	s_nop 1
	v_max_f32_dpp v18, v19, v19 quad_perm:[1,0,3,2] row_mask:0xf bank_mask:0xf bound_ctrl:1
	s_nop 1
	v_max_f32_dpp v18, v18, v18 quad_perm:[2,3,0,1] row_mask:0xf bank_mask:0xf bound_ctrl:1
	s_nop 1
	v_max_f32_dpp v18, v18, v18 row_half_mirror row_mask:0xf bank_mask:0xf bound_ctrl:1
	s_nop 1
	v_max_f32_dpp v18, v18, v18 row_mirror row_mask:0xf bank_mask:0xf bound_ctrl:1
	v_mov_b32_e32 v110, v18
	s_nop 1
	v_permlane16_swap_b32_e32 v110, v18
	v_max_f32_e32 v18, v18, v110
	v_cmp_eq_f32_e32 vcc, v19, v18
	s_nop 1
	v_lshrrev_b64 v[104:105], v166, vcc
	v_ffbl_b32_e32 v104, v104
	v_cmp_ne_u32_e32 vcc, v67, v104
	s_nop 1
	v_cndmask_b32_e32 v108, v233, v19, vcc
	s_nop 1
	v_max_f32_dpp v19, v108, v108 quad_perm:[1,0,3,2] row_mask:0xf bank_mask:0xf bound_ctrl:1
	s_nop 1
	v_max_f32_dpp v19, v19, v19 quad_perm:[2,3,0,1] row_mask:0xf bank_mask:0xf bound_ctrl:1
	s_nop 1
	v_max_f32_dpp v19, v19, v19 row_half_mirror row_mask:0xf bank_mask:0xf bound_ctrl:1
	s_nop 1
	v_max_f32_dpp v19, v19, v19 row_mirror row_mask:0xf bank_mask:0xf bound_ctrl:1
	v_mov_b32_e32 v110, v19
	s_nop 1
	v_permlane16_swap_b32_e32 v110, v19
	v_max_f32_e32 v19, v19, v110
	v_cmp_eq_f32_e32 vcc, v108, v19
	s_nop 1
	v_lshrrev_b64 v[106:107], v166, vcc
	v_ffbl_b32_e32 v105, v106
	v_cmp_ne_u32_e32 vcc, v67, v105
	s_nop 1
	v_cndmask_b32_e32 v109, v233, v108, vcc
	s_nop 1
	v_max_f32_dpp v108, v109, v109 quad_perm:[1,0,3,2] row_mask:0xf bank_mask:0xf bound_ctrl:1
	s_nop 1
	v_max_f32_dpp v108, v108, v108 quad_perm:[2,3,0,1] row_mask:0xf bank_mask:0xf bound_ctrl:1
	s_nop 1
	v_max_f32_dpp v108, v108, v108 row_half_mirror row_mask:0xf bank_mask:0xf bound_ctrl:1
	s_nop 1
	v_max_f32_dpp v108, v108, v108 row_mirror row_mask:0xf bank_mask:0xf bound_ctrl:1
	v_mov_b32_e32 v110, v108
	s_nop 1
	v_permlane16_swap_b32_e32 v110, v108
	v_max_f32_e32 v108, v108, v110
	v_cmp_eq_f32_e32 vcc, v109, v108
	s_nop 1
	v_lshrrev_b64 v[106:107], v166, vcc
	v_ffbl_b32_e32 v106, v106
	v_cmp_ne_u32_e32 vcc, v67, v106
	s_nop 1
	v_cndmask_b32_e32 v107, v233, v109, vcc
	s_nop 1
	v_max_f32_dpp v109, v107, v107 quad_perm:[1,0,3,2] row_mask:0xf bank_mask:0xf bound_ctrl:1
	s_nop 1
	v_max_f32_dpp v109, v109, v109 quad_perm:[2,3,0,1] row_mask:0xf bank_mask:0xf bound_ctrl:1
	s_nop 1
	v_max_f32_dpp v109, v109, v109 row_half_mirror row_mask:0xf bank_mask:0xf bound_ctrl:1
	s_nop 1
	v_max_f32_dpp v109, v109, v109 row_mirror row_mask:0xf bank_mask:0xf bound_ctrl:1
	v_mov_b32_e32 v110, v109
	s_nop 1
	v_permlane16_swap_b32_e32 v110, v109
	v_max_f32_e32 v109, v109, v110
	v_cmp_eq_f32_e32 vcc, v107, v109
	s_and_saveexec_b64 s[2:3], s[48:49]
	s_cbranch_execz .LBB0_823
	v_sub_f32_e32 v109, v109, v18
	v_sub_f32_e32 v108, v108, v18
	v_sub_f32_e32 v18, v19, v18
	v_lshrrev_b64 v[110:111], v166, vcc
	v_mul_f32_e32 v18, 0x3fb8aa3b, v18
	v_ffbl_b32_e32 v107, v110
	v_mul_f32_e32 v108, 0x3fb8aa3b, v108
	v_exp_f32_e32 v110, v18
	v_mul_f32_e32 v109, 0x3fb8aa3b, v109
	v_exp_f32_e32 v111, v108
	v_exp_f32_e32 v109, v109
	v_add_f32_e32 v18, 1.0, v110
	v_add_f32_e32 v18, v18, v111
	v_add_f32_e32 v18, v18, v109
	v_div_scale_f32 v19, s[8:9], v18, v18, 1.0
	v_rcp_f32_e32 v108, v19
	s_nop 0
	v_fma_f32 v112, -v19, v108, 1.0
	v_fmac_f32_e32 v108, v112, v108
	v_div_scale_f32 v112, vcc, 1.0, v18, 1.0
	v_mul_f32_e32 v113, v112, v108
	v_fma_f32 v114, -v19, v113, v112
	v_fmac_f32_e32 v113, v114, v108
	v_fma_f32 v19, -v19, v113, v112
	v_div_fmas_f32 v19, v19, v108, v113
	v_div_fixup_f32 v108, v19, v18, 1.0
	v_add_u32_e32 v18, 0xfffff000, v185
	ds_write_b128 v18, v[104:107]
	v_pk_mul_f32 v[18:19], v[110:111], v[108:109] op_sel_hi:[1,0]
	v_mul_f32_e32 v111, v109, v108
	v_mov_b32_e32 v109, v18
	v_mov_b32_e32 v110, v19
	ds_write_b128 v185, v[108:111]
	v_lshl_add_u32 v18, v104, 2, s26
	ds_add_u32 v18, v201
	v_lshl_add_u32 v18, v105, 2, s26
	ds_add_u32 v18, v201
	v_lshl_add_u32 v18, v106, 2, s26
	ds_add_u32 v18, v201
	v_lshl_add_u32 v18, v107, 2, s26
	ds_add_u32 v18, v201
	s_branch .LBB0_823
